# post_row: the four residual loads of a context row are issued together with counted waits (was one full round trip each)
# speedup vs baseline: 1.0018x; 1.0018x over previous
.LBB0_1835:
	s_or_b64 exec, exec, s[12:13]
	s_lshl_b64 s[12:13], s[22:23], 11
	v_lshl_add_u64 v[12:13], v[58:59], 0, s[12:13]
	global_load_dwordx2 v[62:63], v[12:13], off
	s_waitcnt vmcnt(1)
	ds_bpermute_b32 v1, v37, v0
	s_add_u32 s20, s40, s12
	s_addc_u32 s21, s41, s13
	s_add_i32 s53, s53, s49
	s_cmpk_lt_i32 s22, 0x4000
	s_waitcnt lgkmcnt(0)
	v_add_f32_e32 v0, v0, v1
	ds_bpermute_b32 v1, v78, v0
	s_cselect_b32 s13, s23, 0
	s_cselect_b32 s12, s22, s53
	s_cselect_b32 s0, s25, s27
	s_cselect_b32 s28, s24, s26
	s_waitcnt lgkmcnt(0)
	v_add_f32_e32 v0, v0, v1
	ds_bpermute_b32 v1, v79, v0
	s_lshl_b64 s[12:13], s[12:13], 12
	s_add_u32 s28, s28, s12
	s_addc_u32 s29, s0, s13
	s_and_b64 vcc, exec, s[16:17]
	s_waitcnt lgkmcnt(0)
	v_add_f32_e32 v0, v0, v1
	ds_bpermute_b32 v1, v80, v0
	v_lshlrev_b32_e32 v87, 1, v32
	s_waitcnt lgkmcnt(0)
	v_add_f32_e32 v0, v0, v1
	ds_bpermute_b32 v1, v81, v0
	s_waitcnt lgkmcnt(0)
	v_add_f32_e32 v70, v0, v1
	ds_bpermute_b32 v71, v82, v70
	s_cbranch_vccz .LBB0_1850
	global_load_dwordx2 v[2:3], v87, s[20:21] nt
	global_load_dwordx2 v[6:7], v87, s[20:21] offset:512 nt
	global_load_dwordx2 v[10:11], v87, s[20:21] offset:1024 nt
	global_load_dwordx2 v[14:15], v87, s[20:21] offset:1536 nt
	s_waitcnt vmcnt(3)
	v_lshlrev_b32_e32 v0, 16, v2
	v_and_b32_e32 v1, 0xffff0000, v2
	v_lshlrev_b32_e32 v2, 16, v3
	v_and_b32_e32 v3, 0xffff0000, v3
	v_lshlrev_b32_e32 v86, 2, v32
	s_cbranch_execnz .LBB0_1838

.LBB0_1838:
	global_load_dwordx2 v[64:65], v[12:13], off offset:512
	v_cndmask_b32_e64 v4, 0, 1, s[16:17]
	v_cmp_ne_u32_e64 s[12:13], 1, v4
	s_andn2_b64 vcc, exec, s[16:17]
	s_cbranch_vccnz .LBB0_1851
	s_waitcnt vmcnt(3)
	v_lshlrev_b32_e32 v4, 16, v6
	v_and_b32_e32 v5, 0xffff0000, v6
	v_lshlrev_b32_e32 v6, 16, v7
	v_and_b32_e32 v7, 0xffff0000, v7
	s_cbranch_execnz .LBB0_1841

.LBB0_1841:
	global_load_dwordx2 v[66:67], v[12:13], off offset:1024
	s_and_b64 vcc, exec, s[12:13]
	s_cbranch_vccnz .LBB0_1852
	s_waitcnt vmcnt(3)
	v_lshlrev_b32_e32 v8, 16, v10
	v_and_b32_e32 v9, 0xffff0000, v10
	v_lshlrev_b32_e32 v10, 16, v11
	v_and_b32_e32 v11, 0xffff0000, v11
	s_cbranch_execnz .LBB0_1844

.LBB0_1844:
	global_load_dwordx2 v[68:69], v[12:13], off offset:1536
	s_and_b64 vcc, exec, s[12:13]
	s_cbranch_vccnz .LBB0_1853
	s_waitcnt vmcnt(3)
	v_lshlrev_b32_e32 v12, 16, v14
	v_and_b32_e32 v13, 0xffff0000, v14
	v_lshlrev_b32_e32 v14, 16, v15
	v_and_b32_e32 v15, 0xffff0000, v15
	s_lshl_b64 s[12:13], s[22:23], 10
	s_cbranch_execnz .LBB0_1847
